# v46 with the P2 GEMM-side throttle reduced to s_sleep 24 (margin for other chips)
# baseline (speedup 1.0000x reference)
.LBB0_255:
	ds_read_b128 v[128:131], v182
	ds_read_b128 v[132:135], v182 offset:1024
	ds_read_b128 v[136:139], v182 offset:2048
	ds_read_b128 v[140:143], v182 offset:3072
	ds_read_b128 v[164:167], v183
	ds_read_b128 v[168:171], v183 offset:1024
	ds_read_b128 v[172:175], v183 offset:2048
	ds_read_b128 v[186:189], v183 offset:3072
	s_add_u32 s28, s0, 0xfffc0080
	s_addc_u32 s29, s1, -1
	s_cmp_eq_u32 s58, 12
	s_cselect_b32 s31, s23, s29
	s_cselect_b32 s30, s54, s28
	s_cselect_b32 s29, s21, s57
	s_cselect_b32 s28, s55, s56
	v_lshl_add_u64 v[176:177], s[0:1], 0, v[156:157]
	s_add_i32 m0, s39, 0xc000
	ds_read_b128 v[190:193], v184
	ds_read_b128 v[194:197], v184 offset:1024
	ds_read_b128 v[198:201], v184 offset:2048
	ds_read_b128 v[202:205], v184 offset:3072
	ds_read_b128 v[206:209], v184 offset:4096
	ds_read_b128 v[210:213], v184 offset:5120
	ds_read_b128 v[214:217], v184 offset:6144
	ds_read_b128 v[218:221], v184 offset:7168
	global_load_lds_dwordx4 v[176:177], off
	v_lshl_add_u64 v[176:177], s[0:1], 0, v[158:159]
	s_add_i32 m0, s39, 0xe000
	s_nop 0
	global_load_lds_dwordx4 v[176:177], off
	s_waitcnt vmcnt(8)
	s_waitcnt lgkmcnt(0)
	s_barrier
	s_setprio 1
	s_waitcnt lgkmcnt(0)
	v_mfma_f32_16x16x32_bf16 v[124:127], v[128:131], v[190:193], v[124:127]
	v_mfma_f32_16x16x32_bf16 v[120:123], v[136:139], v[190:193], v[120:123]
	v_mfma_f32_16x16x32_bf16 v[116:119], v[128:131], v[198:201], v[116:119]
	v_mfma_f32_16x16x32_bf16 v[108:111], v[136:139], v[198:201], v[108:111]
	v_mfma_f32_16x16x32_bf16 v[100:103], v[128:131], v[206:209], v[100:103]
	v_mfma_f32_16x16x32_bf16 v[92:95], v[136:139], v[206:209], v[92:95]
	v_mfma_f32_16x16x32_bf16 v[84:87], v[128:131], v[214:217], v[84:87]
	v_mfma_f32_16x16x32_bf16 v[76:79], v[136:139], v[214:217], v[76:79]
	v_mfma_f32_16x16x32_bf16 v[124:127], v[132:135], v[194:197], v[124:127]
	v_mfma_f32_16x16x32_bf16 v[120:123], v[140:143], v[194:197], v[120:123]
	v_mfma_f32_16x16x32_bf16 v[116:119], v[132:135], v[202:205], v[116:119]
	v_mfma_f32_16x16x32_bf16 v[108:111], v[140:143], v[202:205], v[108:111]
	v_mfma_f32_16x16x32_bf16 v[100:103], v[132:135], v[210:213], v[100:103]
	v_mfma_f32_16x16x32_bf16 v[92:95], v[140:143], v[210:213], v[92:95]
	v_mfma_f32_16x16x32_bf16 v[84:87], v[132:135], v[218:221], v[84:87]
	v_mfma_f32_16x16x32_bf16 v[76:79], v[140:143], v[218:221], v[76:79]
	s_setprio 0
	s_setprio 1
	v_mfma_f32_16x16x32_bf16 v[112:115], v[164:167], v[190:193], v[112:115]
	v_mfma_f32_16x16x32_bf16 v[104:107], v[172:175], v[190:193], v[104:107]
	v_mfma_f32_16x16x32_bf16 v[96:99], v[164:167], v[198:201], v[96:99]
	v_mfma_f32_16x16x32_bf16 v[88:91], v[172:175], v[198:201], v[88:91]
	v_mfma_f32_16x16x32_bf16 v[80:83], v[164:167], v[206:209], v[80:83]
	v_mfma_f32_16x16x32_bf16 v[72:75], v[172:175], v[206:209], v[72:75]
	v_mfma_f32_16x16x32_bf16 v[68:71], v[164:167], v[214:217], v[68:71]
	v_mfma_f32_16x16x32_bf16 v[64:67], v[172:175], v[214:217], v[64:67]
	v_mfma_f32_16x16x32_bf16 v[112:115], v[168:171], v[194:197], v[112:115]
	v_mfma_f32_16x16x32_bf16 v[104:107], v[186:189], v[194:197], v[104:107]
	v_mfma_f32_16x16x32_bf16 v[96:99], v[168:171], v[202:205], v[96:99]
	v_mfma_f32_16x16x32_bf16 v[88:91], v[186:189], v[202:205], v[88:91]
	v_mfma_f32_16x16x32_bf16 v[80:83], v[168:171], v[210:213], v[80:83]
	v_mfma_f32_16x16x32_bf16 v[72:75], v[186:189], v[210:213], v[72:75]
	v_mfma_f32_16x16x32_bf16 v[68:71], v[168:171], v[218:221], v[68:71]
	v_mfma_f32_16x16x32_bf16 v[64:67], v[186:189], v[218:221], v[64:67]
	s_setprio 0
	s_barrier
	s_add_i32 s59, s47, s38
	v_lshl_add_u64 v[176:177], s[28:29], 0, v[148:149]
	s_mov_b32 m0, s59
	ds_read_b128 v[190:193], v184 offset:16384
	ds_read_b128 v[194:197], v184 offset:17408
	ds_read_b128 v[198:201], v184 offset:18432
	ds_read_b128 v[202:205], v184 offset:19456
	ds_read_b128 v[206:209], v184 offset:20480
	ds_read_b128 v[210:213], v184 offset:21504
	ds_read_b128 v[214:217], v184 offset:22528
	ds_read_b128 v[218:221], v184 offset:23552
	global_load_lds_dwordx4 v[176:177], off
	s_add_i32 m0, s59, 0x2000
	s_add_u32 s60, s28, 0x40000
	v_lshl_add_u64 v[222:223], s[28:29], 0, v[144:145]
	s_addc_u32 s61, s29, 0
	s_add_i32 s59, s48, s38
	global_load_lds_dwordx4 v[222:223], off
	v_lshl_add_u64 v[224:225], s[60:61], 0, v[148:149]
	s_mov_b32 m0, s59
	v_lshl_add_u64 v[226:227], s[30:31], 0, v[146:147]
	global_load_lds_dwordx4 v[224:225], off
	v_lshl_add_u64 v[224:225], s[60:61], 0, v[144:145]
	s_add_i32 m0, s59, 0x2000
	s_nop 0
	global_load_lds_dwordx4 v[224:225], off
	v_lshl_add_u64 v[224:225], s[30:31], 0, v[150:151]
	s_mov_b32 m0, s39
	s_nop 0
	global_load_lds_dwordx4 v[224:225], off
	s_mov_b32 m0, s40
	s_nop 0
	global_load_lds_dwordx4 v[226:227], off
	s_waitcnt vmcnt(8)
	s_waitcnt lgkmcnt(0)
	s_barrier
	s_setprio 1
	s_waitcnt lgkmcnt(0)
	v_mfma_f32_16x16x32_bf16 v[60:63], v[128:131], v[190:193], v[60:63]
	v_mfma_f32_16x16x32_bf16 v[56:59], v[136:139], v[190:193], v[56:59]
	v_mfma_f32_16x16x32_bf16 v[52:55], v[128:131], v[198:201], v[52:55]
	v_mfma_f32_16x16x32_bf16 v[44:47], v[136:139], v[198:201], v[44:47]
	v_mfma_f32_16x16x32_bf16 v[36:39], v[128:131], v[206:209], v[36:39]
	v_mfma_f32_16x16x32_bf16 v[28:31], v[136:139], v[206:209], v[28:31]
	v_mfma_f32_16x16x32_bf16 v[20:23], v[128:131], v[214:217], v[20:23]
	v_mfma_f32_16x16x32_bf16 v[12:15], v[136:139], v[214:217], v[12:15]
	v_mfma_f32_16x16x32_bf16 v[60:63], v[132:135], v[194:197], v[60:63]
	v_mfma_f32_16x16x32_bf16 v[56:59], v[140:143], v[194:197], v[56:59]
	v_mfma_f32_16x16x32_bf16 v[52:55], v[132:135], v[202:205], v[52:55]
	v_mfma_f32_16x16x32_bf16 v[44:47], v[140:143], v[202:205], v[44:47]
	v_mfma_f32_16x16x32_bf16 v[36:39], v[132:135], v[210:213], v[36:39]
	v_mfma_f32_16x16x32_bf16 v[28:31], v[140:143], v[210:213], v[28:31]
	v_mfma_f32_16x16x32_bf16 v[20:23], v[132:135], v[218:221], v[20:23]
	v_mfma_f32_16x16x32_bf16 v[12:15], v[140:143], v[218:221], v[12:15]
	s_setprio 0
	s_setprio 1
	v_mfma_f32_16x16x32_bf16 v[48:51], v[164:167], v[190:193], v[48:51]
	v_mfma_f32_16x16x32_bf16 v[40:43], v[172:175], v[190:193], v[40:43]
	v_mfma_f32_16x16x32_bf16 v[32:35], v[164:167], v[198:201], v[32:35]
	v_mfma_f32_16x16x32_bf16 v[24:27], v[172:175], v[198:201], v[24:27]
	v_mfma_f32_16x16x32_bf16 v[16:19], v[164:167], v[206:209], v[16:19]
	v_mfma_f32_16x16x32_bf16 v[8:11], v[172:175], v[206:209], v[8:11]
	v_mfma_f32_16x16x32_bf16 v[4:7], v[164:167], v[214:217], v[4:7]
	v_mfma_f32_16x16x32_bf16 v[0:3], v[172:175], v[214:217], v[0:3]
	v_mfma_f32_16x16x32_bf16 v[48:51], v[168:171], v[194:197], v[48:51]
	v_mfma_f32_16x16x32_bf16 v[40:43], v[186:189], v[194:197], v[40:43]
	v_mfma_f32_16x16x32_bf16 v[32:35], v[168:171], v[202:205], v[32:35]
	v_mfma_f32_16x16x32_bf16 v[24:27], v[186:189], v[202:205], v[24:27]
	v_mfma_f32_16x16x32_bf16 v[16:19], v[168:171], v[210:213], v[16:19]
	v_mfma_f32_16x16x32_bf16 v[8:11], v[186:189], v[210:213], v[8:11]
	v_mfma_f32_16x16x32_bf16 v[4:7], v[168:171], v[218:221], v[4:7]
	v_mfma_f32_16x16x32_bf16 v[0:3], v[186:189], v[218:221], v[0:3]
	s_setprio 0
	s_barrier
	s_add_i32 s59, 0, 0x18000
	s_add_i32 s60, 0, 0x1c000
	v_add_u32_e32 v140, s59, v180
	v_add_u32_e32 v152, s60, v180
	ds_read_b128 v[128:131], v140
	ds_read_b128 v[132:135], v140 offset:1024
	ds_read_b128 v[136:139], v140 offset:2048
	ds_read_b128 v[140:143], v140 offset:3072
	ds_read_b128 v[164:167], v152
	ds_read_b128 v[168:171], v152 offset:1024
	ds_read_b128 v[172:175], v152 offset:2048
	ds_read_b128 v[186:189], v152 offset:3072
	s_add_u32 s30, s30, 0x40000
	s_addc_u32 s31, s31, 0
	s_mov_b32 m0, s41
	v_lshl_add_u64 v[228:229], s[30:31], 0, v[150:151]
	ds_read_b128 v[190:193], v184 offset:32768
	ds_read_b128 v[194:197], v184 offset:33792
	ds_read_b128 v[198:201], v184 offset:34816
	ds_read_b128 v[202:205], v184 offset:35840
	ds_read_b128 v[206:209], v184 offset:36864
	ds_read_b128 v[210:213], v184 offset:37888
	ds_read_b128 v[214:217], v184 offset:38912
	ds_read_b128 v[218:221], v184 offset:39936
	global_load_lds_dwordx4 v[228:229], off
	v_lshl_add_u64 v[228:229], s[30:31], 0, v[146:147]
	s_mov_b32 m0, s42
	s_nop 0
	global_load_lds_dwordx4 v[228:229], off
	s_waitcnt vmcnt(8)
	s_waitcnt lgkmcnt(0)
	s_barrier
	s_setprio 1
	s_waitcnt lgkmcnt(0)
	v_mfma_f32_16x16x32_bf16 v[124:127], v[128:131], v[190:193], v[124:127]
	v_mfma_f32_16x16x32_bf16 v[120:123], v[136:139], v[190:193], v[120:123]
	v_mfma_f32_16x16x32_bf16 v[116:119], v[128:131], v[198:201], v[116:119]
	v_mfma_f32_16x16x32_bf16 v[108:111], v[136:139], v[198:201], v[108:111]
	v_mfma_f32_16x16x32_bf16 v[100:103], v[128:131], v[206:209], v[100:103]
	v_mfma_f32_16x16x32_bf16 v[92:95], v[136:139], v[206:209], v[92:95]
	v_mfma_f32_16x16x32_bf16 v[84:87], v[128:131], v[214:217], v[84:87]
	v_mfma_f32_16x16x32_bf16 v[76:79], v[136:139], v[214:217], v[76:79]
	v_mfma_f32_16x16x32_bf16 v[124:127], v[132:135], v[194:197], v[124:127]
	v_mfma_f32_16x16x32_bf16 v[120:123], v[140:143], v[194:197], v[120:123]
	v_mfma_f32_16x16x32_bf16 v[116:119], v[132:135], v[202:205], v[116:119]
	v_mfma_f32_16x16x32_bf16 v[108:111], v[140:143], v[202:205], v[108:111]
	v_mfma_f32_16x16x32_bf16 v[100:103], v[132:135], v[210:213], v[100:103]
	v_mfma_f32_16x16x32_bf16 v[92:95], v[140:143], v[210:213], v[92:95]
	v_mfma_f32_16x16x32_bf16 v[84:87], v[132:135], v[218:221], v[84:87]
	v_mfma_f32_16x16x32_bf16 v[76:79], v[140:143], v[218:221], v[76:79]
	s_setprio 0
	s_setprio 1
	v_mfma_f32_16x16x32_bf16 v[112:115], v[164:167], v[190:193], v[112:115]
	v_mfma_f32_16x16x32_bf16 v[104:107], v[172:175], v[190:193], v[104:107]
	v_mfma_f32_16x16x32_bf16 v[96:99], v[164:167], v[198:201], v[96:99]
	v_mfma_f32_16x16x32_bf16 v[88:91], v[172:175], v[198:201], v[88:91]
	v_mfma_f32_16x16x32_bf16 v[80:83], v[164:167], v[206:209], v[80:83]
	v_mfma_f32_16x16x32_bf16 v[72:75], v[172:175], v[206:209], v[72:75]
	v_mfma_f32_16x16x32_bf16 v[68:71], v[164:167], v[214:217], v[68:71]
	v_mfma_f32_16x16x32_bf16 v[64:67], v[172:175], v[214:217], v[64:67]
	v_mfma_f32_16x16x32_bf16 v[112:115], v[168:171], v[194:197], v[112:115]
	v_mfma_f32_16x16x32_bf16 v[104:107], v[186:189], v[194:197], v[104:107]
	v_mfma_f32_16x16x32_bf16 v[96:99], v[168:171], v[202:205], v[96:99]
	v_mfma_f32_16x16x32_bf16 v[88:91], v[186:189], v[202:205], v[88:91]
	v_mfma_f32_16x16x32_bf16 v[80:83], v[168:171], v[210:213], v[80:83]
	v_mfma_f32_16x16x32_bf16 v[72:75], v[186:189], v[210:213], v[72:75]
	v_mfma_f32_16x16x32_bf16 v[68:71], v[168:171], v[218:221], v[68:71]
	v_mfma_f32_16x16x32_bf16 v[64:67], v[186:189], v[218:221], v[64:67]
	s_setprio 0
	s_barrier
	s_add_i32 s30, s59, s38
	v_lshl_add_u64 v[176:177], v[176:177], 0, s[10:11]
	s_mov_b32 m0, s30
	ds_read_b128 v[190:193], v184 offset:49152
	ds_read_b128 v[194:197], v184 offset:50176
	ds_read_b128 v[198:201], v184 offset:51200
	ds_read_b128 v[202:205], v184 offset:52224
	ds_read_b128 v[206:209], v184 offset:53248
	ds_read_b128 v[210:213], v184 offset:54272
	ds_read_b128 v[214:217], v184 offset:55296
	ds_read_b128 v[218:221], v184 offset:56320
	global_load_lds_dwordx4 v[176:177], off
	s_add_i32 m0, s30, 0x2000
	s_add_u32 s28, s28, 0x40080
	v_lshl_add_u64 v[176:177], v[222:223], 0, s[10:11]
	s_addc_u32 s29, s29, 0
	s_add_i32 s30, s60, s38
	global_load_lds_dwordx4 v[176:177], off
	v_lshl_add_u64 v[176:177], s[28:29], 0, v[148:149]
	s_mov_b32 m0, s30
	s_nop 0
	global_load_lds_dwordx4 v[176:177], off
	v_lshl_add_u64 v[176:177], s[28:29], 0, v[144:145]
	s_add_i32 m0, s30, 0x2000
	s_nop 0
	global_load_lds_dwordx4 v[176:177], off
	v_lshl_add_u64 v[176:177], v[224:225], 0, s[10:11]
	s_mov_b32 m0, s44
	s_nop 0
	global_load_lds_dwordx4 v[176:177], off
	v_lshl_add_u64 v[176:177], v[226:227], 0, s[10:11]
	s_mov_b32 m0, s45
	s_nop 0
	global_load_lds_dwordx4 v[176:177], off
	s_waitcnt vmcnt(8)
	s_waitcnt lgkmcnt(0)
	s_barrier
	s_setprio 1
	s_waitcnt lgkmcnt(0)
	v_mfma_f32_16x16x32_bf16 v[60:63], v[128:131], v[190:193], v[60:63]
	v_mfma_f32_16x16x32_bf16 v[56:59], v[136:139], v[190:193], v[56:59]
	v_mfma_f32_16x16x32_bf16 v[52:55], v[128:131], v[198:201], v[52:55]
	v_mfma_f32_16x16x32_bf16 v[44:47], v[136:139], v[198:201], v[44:47]
	v_mfma_f32_16x16x32_bf16 v[36:39], v[128:131], v[206:209], v[36:39]
	v_mfma_f32_16x16x32_bf16 v[28:31], v[136:139], v[206:209], v[28:31]
	v_mfma_f32_16x16x32_bf16 v[20:23], v[128:131], v[214:217], v[20:23]
	v_mfma_f32_16x16x32_bf16 v[12:15], v[136:139], v[214:217], v[12:15]
	v_mfma_f32_16x16x32_bf16 v[60:63], v[132:135], v[194:197], v[60:63]
	v_mfma_f32_16x16x32_bf16 v[56:59], v[140:143], v[194:197], v[56:59]
	v_mfma_f32_16x16x32_bf16 v[52:55], v[132:135], v[202:205], v[52:55]
	v_mfma_f32_16x16x32_bf16 v[44:47], v[140:143], v[202:205], v[44:47]
	v_mfma_f32_16x16x32_bf16 v[36:39], v[132:135], v[210:213], v[36:39]
	v_mfma_f32_16x16x32_bf16 v[28:31], v[140:143], v[210:213], v[28:31]
	v_mfma_f32_16x16x32_bf16 v[20:23], v[132:135], v[218:221], v[20:23]
	v_mfma_f32_16x16x32_bf16 v[12:15], v[140:143], v[218:221], v[12:15]
	s_setprio 0
	s_setprio 1
	v_mfma_f32_16x16x32_bf16 v[48:51], v[164:167], v[190:193], v[48:51]
	v_mfma_f32_16x16x32_bf16 v[40:43], v[172:175], v[190:193], v[40:43]
	v_mfma_f32_16x16x32_bf16 v[32:35], v[164:167], v[198:201], v[32:35]
	v_mfma_f32_16x16x32_bf16 v[24:27], v[172:175], v[198:201], v[24:27]
	v_mfma_f32_16x16x32_bf16 v[16:19], v[164:167], v[206:209], v[16:19]
	v_mfma_f32_16x16x32_bf16 v[8:11], v[172:175], v[206:209], v[8:11]
	v_mfma_f32_16x16x32_bf16 v[4:7], v[164:167], v[214:217], v[4:7]
	v_mfma_f32_16x16x32_bf16 v[0:3], v[172:175], v[214:217], v[0:3]
	v_mfma_f32_16x16x32_bf16 v[48:51], v[168:171], v[194:197], v[48:51]
	v_mfma_f32_16x16x32_bf16 v[40:43], v[186:189], v[194:197], v[40:43]
	v_mfma_f32_16x16x32_bf16 v[32:35], v[168:171], v[202:205], v[32:35]
	v_mfma_f32_16x16x32_bf16 v[24:27], v[186:189], v[202:205], v[24:27]
	v_mfma_f32_16x16x32_bf16 v[16:19], v[168:171], v[210:213], v[16:19]
	v_mfma_f32_16x16x32_bf16 v[8:11], v[186:189], v[210:213], v[8:11]
	v_mfma_f32_16x16x32_bf16 v[4:7], v[168:171], v[218:221], v[4:7]
	v_mfma_f32_16x16x32_bf16 v[0:3], v[186:189], v[218:221], v[0:3]
	s_setprio 0
	s_barrier
	s_add_i32 s58, s58, 2
	s_add_u32 s0, s0, 0x100
	s_addc_u32 s1, s1, 0
	s_add_u32 s56, s56, 0x100
	s_addc_u32 s57, s57, 0
	s_cmp_gt_u32 s58, 13
	s_sleep 24
	s_cbranch_scc0 .LBB0_255
	s_and_b64 vcc, exec, s[12:13]
	s_cbranch_vccz .LBB0_258
	s_barrier
